# ret_out gate loads issued right after q MFMAs (hidden under QK/PV compute)
# speedup vs baseline: 1.0526x; 1.0074x over previous
.LBB0_722:
	s_or_b64 exec, exec, s[0:1]
	ds_read_b128 v[84:87], v81 offset:36864
	ds_read_b128 v[88:91], v81 offset:36928
	s_lshl_b32 s0, s88, 6
	v_lshlrev_b64 v[100:101], 9, v[40:41]
	s_lshl_b32 s2, s0, 1
	s_mov_b64 s[0:1], 0x119a4400
	s_add_i32 s33, s33, s90
	v_lshl_add_u64 v[34:35], v[34:35], 0, s[86:87]
	s_waitcnt lgkmcnt(1)
	v_mfma_f32_16x16x32_bf16 v[84:87], v[84:87], v[4:7], 0
	ds_read_b128 v[92:95], v81 offset:39232
	ds_read_b128 v[96:99], v81 offset:41536
	s_waitcnt lgkmcnt(2)
	v_mfma_f32_16x16x32_bf16 v[84:87], v[88:91], v[0:3], v[84:87]
	ds_read_b128 v[88:91], v81 offset:39168
	s_waitcnt lgkmcnt(0)
	v_mfma_f32_16x16x32_bf16 v[88:91], v[88:91], v[4:7], 0
	v_mfma_f32_16x16x32_bf16 v[88:91], v[92:95], v[0:3], v[88:91]
	ds_read_b128 v[92:95], v81 offset:41472
	s_waitcnt lgkmcnt(0)
	v_mfma_f32_16x16x32_bf16 v[92:95], v[92:95], v[4:7], 0
	v_mfma_f32_16x16x32_bf16 v[92:95], v[96:99], v[0:3], v[92:95]
	ds_read_b128 v[96:99], v81 offset:43776
	s_waitcnt lgkmcnt(0)
	v_mfma_f32_16x16x32_bf16 v[4:7], v[96:99], v[4:7], 0
	ds_read_b128 v[96:99], v81 offset:43840
	s_waitcnt lgkmcnt(0)
	v_mfma_f32_16x16x32_bf16 v[2:5], v[96:99], v[0:3], v[4:7]
	v_mul_f32_e32 v0, v39, v75
	s_nop 3
	v_exp_f32_e32 v6, v0
	v_mov_b32_e32 v39, v25
	v_pk_fma_f32 v[22:23], v[6:7], v[86:87], v[22:23] op_sel_hi:[0,1,1]
	v_pk_fma_f32 v[20:21], v[6:7], v[84:85], v[20:21] op_sel_hi:[0,1,1]
	v_pk_mul_f32 v[0:1], v[22:23], v[22:23]
	v_pk_mul_f32 v[84:85], v[20:21], v[20:21]
	v_pk_fma_f32 v[14:15], v[6:7], v[90:91], v[14:15] op_sel_hi:[0,1,1]
	v_pk_mov_b32 v[86:87], v[84:85], v[0:1] op_sel:[1,0]
	v_mov_b32_e32 v85, v1
	v_pk_fma_f32 v[12:13], v[6:7], v[88:89], v[12:13] op_sel_hi:[0,1,1]
	v_pk_add_f32 v[84:85], v[86:87], v[84:85]
	v_pk_mul_f32 v[0:1], v[14:15], v[14:15]
	v_pk_mul_f32 v[86:87], v[12:13], v[12:13]
	v_pk_fma_f32 v[2:3], v[6:7], v[2:3], v[16:17] op_sel_hi:[0,1,1]
	v_pk_mov_b32 v[88:89], v[86:87], v[0:1] op_sel:[1,0]
	v_mov_b32_e32 v87, v1
	v_pk_add_f32 v[86:87], v[88:89], v[86:87]
	v_pk_fma_f32 v[10:11], v[6:7], v[94:95], v[10:11] op_sel_hi:[0,1,1]
	v_pk_fma_f32 v[8:9], v[6:7], v[92:93], v[8:9] op_sel_hi:[0,1,1]
	v_pk_fma_f32 v[0:1], v[6:7], v[4:5], v[18:19] op_sel_hi:[0,1,1]
	v_mul_f32_e32 v6, v2, v2
	v_pk_add_f32 v[4:5], v[84:85], v[84:85] op_sel:[0,1] op_sel_hi:[1,0]
	v_mul_f32_e32 v16, v3, v3
	v_mov_b32_e32 v5, v6
	v_pk_add_f32 v[6:7], v[86:87], v[86:87] op_sel:[0,1] op_sel_hi:[1,0]
	v_mul_f32_e32 v17, v0, v0
	v_mov_b32_e32 v7, v16
	v_pk_add_f32 v[4:5], v[4:5], v[6:7]
	v_mul_f32_e32 v6, v9, v9
	v_pk_fma_f32 v[6:7], v[8:9], v[8:9], v[6:7] op_sel_hi:[1,1,0]
	v_mul_f32_e32 v16, v11, v11
	v_mul_f32_e32 v18, v1, v1
	v_mov_b32_e32 v7, v17
	v_pk_fma_f32 v[16:17], v[10:11], v[10:11], v[16:17] op_sel_hi:[1,1,0]
	s_nop 0
	v_mov_b32_e32 v17, v18
	v_pk_add_f32 v[6:7], v[6:7], v[16:17]
	s_nop 0
	v_pk_add_f32 v[4:5], v[4:5], v[6:7]
	v_lshl_add_u64 v[6:7], v[100:101], 1, s[96:97]
	v_lshl_add_u64 v[6:7], v[6:7], 0, s[2:3]
	v_lshl_add_u64 v[16:17], v[6:7], 0, v[38:39]
	v_lshlrev_b64 v[6:7], 11, v[40:41]
	s_nop 0
	v_add_f32_e32 v4, v4, v5
	ds_bpermute_b32 v5, v76, v4
	v_lshl_add_u64 v[6:7], s[22:23], 0, v[6:7]
	v_lshl_add_u64 v[6:7], v[6:7], 0, s[2:3]
	v_lshl_add_u64 v[18:19], v[6:7], 0, v[38:39]
	v_lshl_add_u64 v[6:7], v[18:19], 0, s[0:1]
	s_waitcnt lgkmcnt(0)
	v_add_f32_e32 v4, v4, v5
	ds_bpermute_b32 v5, v77, v4
	s_mov_b32 s0, 0x119a4000
	v_add_co_u32_e64 v18, s[0:1], s0, v18
	s_waitcnt lgkmcnt(0)
	v_add_f32_e32 v4, v4, v5
	v_fmamk_f32 v4, v4, 0x3c800000, v82
	v_rsq_f32_e32 v4, v4
	v_addc_co_u32_e64 v19, s[0:1], 0, v19, s[0:1]
	v_readlane_b32 s0, v246, 1
	v_pk_mul_f32 v[20:21], v[20:21], v[4:5] op_sel_hi:[1,0]
	v_pk_mul_f32 v[22:23], v[22:23], v[4:5] op_sel_hi:[1,0]
	v_pk_mul_f32 v[12:13], v[12:13], v[4:5] op_sel_hi:[1,0]
	v_pk_mul_f32 v[14:15], v[14:15], v[4:5] op_sel_hi:[1,0]
	v_pk_mul_f32 v[8:9], v[8:9], v[4:5] op_sel_hi:[1,0]
	v_pk_mul_f32 v[10:11], v[10:11], v[4:5] op_sel_hi:[1,0]
	v_pk_mul_f32 v[2:3], v[2:3], v[4:5] op_sel_hi:[1,0]
	v_pk_mul_f32 v[0:1], v[0:1], v[4:5] op_sel_hi:[1,0]
	s_add_i32 s91, s91, s0
	s_cmpk_lt_i32 s91, 0x800
	v_readlane_b32 s1, v246, 2
	s_waitcnt vmcnt(0)
	v_mov_b32_e32 v40, v140
	v_mov_b32_e32 v41, v141
	v_lshlrev_b32_e32 v84, 16, v40
	v_and_b32_e32 v85, 0xffff0000, v40
	v_lshlrev_b32_e32 v40, 16, v41
	v_and_b32_e32 v41, 0xffff0000, v41
	v_pk_mul_f32 v[20:21], v[20:21], v[84:85]
	v_pk_mul_f32 v[22:23], v[22:23], v[40:41]
	v_cvt_pk_bf16_f32 v20, v20, v21
	v_cvt_pk_bf16_f32 v21, v22, v23
	global_store_dwordx2 v[18:19], v[20:21], off offset:1024
	s_nop 1
	v_mov_b32_e32 v18, v142
	v_mov_b32_e32 v19, v143
	v_lshlrev_b32_e32 v20, 16, v18
	v_and_b32_e32 v21, 0xffff0000, v18
	v_lshlrev_b32_e32 v18, 16, v19
	v_and_b32_e32 v19, 0xffff0000, v19
	v_pk_mul_f32 v[12:13], v[12:13], v[20:21]
	v_pk_mul_f32 v[14:15], v[14:15], v[18:19]
	v_cvt_pk_bf16_f32 v12, v12, v13
	v_cvt_pk_bf16_f32 v13, v14, v15
	global_store_dwordx2 v[6:7], v[12:13], off offset:32
	s_nop 1
	v_mov_b32_e32 v12, v144
	v_mov_b32_e32 v13, v145
	v_lshlrev_b32_e32 v14, 16, v12
	v_and_b32_e32 v15, 0xffff0000, v12
	v_lshlrev_b32_e32 v12, 16, v13
	v_and_b32_e32 v13, 0xffff0000, v13
	v_pk_mul_f32 v[8:9], v[8:9], v[14:15]
	v_pk_mul_f32 v[10:11], v[10:11], v[12:13]
	v_cvt_pk_bf16_f32 v8, v8, v9
	v_cvt_pk_bf16_f32 v9, v10, v11
	global_store_dwordx2 v[6:7], v[8:9], off offset:64
	s_nop 1
	v_mov_b32_e32 v8, v146
	v_mov_b32_e32 v9, v147
	v_lshlrev_b32_e32 v10, 16, v8
	v_and_b32_e32 v11, 0xffff0000, v8
	v_lshlrev_b32_e32 v4, 16, v9
	v_and_b32_e32 v5, 0xffff0000, v9
	v_pk_mul_f32 v[2:3], v[2:3], v[10:11]
	v_pk_mul_f32 v[0:1], v[0:1], v[4:5]
	v_cvt_pk_bf16_f32 v2, v2, v3
	v_cvt_pk_bf16_f32 v3, v0, v1
	global_store_dwordx2 v[6:7], v[2:3], off offset:96
	s_cbranch_scc0 .LBB0_743
.LBB0_723:
	s_bfe_u32 s88, s91, 0x30005
	v_cvt_f32_ubyte0_e32 v0, s88
	v_sub_f32_e32 v0, 0xc0a00000, v0
	s_mov_b32 s0, 0xc2fc0000
	v_cmp_gt_f32_e64 s[0:1], s0, v0
	s_ashr_i32 s92, s91, 8
	s_waitcnt vmcnt(0)
	v_cndmask_b32_e64 v1, 0, v27, s[0:1]
	v_add_f32_e32 v0, v0, v1
	v_exp_f32_e32 v0, v0
	s_and_b64 s[0:1], s[0:1], exec
	s_cselect_b32 s0, 0xffffffc0, 0
	s_ashr_i32 s93, s92, 31
	v_ldexp_f32 v0, v0, s0
	s_lshl_b64 s[0:1], s[92:93], 12
	s_and_b32 s89, s33, 0xf80
	s_or_b32 s92, s0, s89
	v_sub_f32_e32 v10, 1.0, v0
	s_lshl_b32 s2, s88, 7
	v_mov_b32_e32 v1, s1
	v_or_b32_e32 v0, s92, v26
	v_lshl_add_u64 v[4:5], v[30:31], 0, s[2:3]
	v_lshlrev_b64 v[8:9], 10, v[0:1]
	v_lshl_add_u64 v[0:1], v[4:5], 0, v[8:9]
	global_load_dwordx4 v[120:123], v[0:1], off nt
	v_lshl_add_u64 v[6:7], v[32:33], 0, s[2:3]
	s_mov_b32 s93, s1
	v_add_u32_e32 v24, s89, v42
	v_lshl_add_u64 v[40:41], s[0:1], 0, v[24:25]
	v_log_f32_e32 v39, v10
	v_lshl_add_u64 v[0:1], v[6:7], 0, v[8:9]
	global_load_dwordx4 v[124:127], v[0:1], off nt
	v_lshl_add_u64 v[0:1], s[92:93], 0, v[28:29]
	v_lshlrev_b64 v[8:9], 10, v[0:1]
	v_lshl_add_u64 v[0:1], v[4:5], 0, v[8:9]
	global_load_dwordx4 v[128:131], v[0:1], off nt
	v_lshl_add_u64 v[0:1], v[6:7], 0, v[8:9]
	global_load_dwordx4 v[132:135], v[0:1], off nt
	global_load_dwordx4 v[136:139], v[34:35], off nt
	v_lshlrev_b64 v[0:1], 10, v[40:41]
	v_lshl_add_u64 v[0:1], s[94:95], 0, v[0:1]
	v_lshl_add_u64 v[0:1], v[0:1], 0, s[2:3]
	v_lshl_add_u64 v[0:1], v[0:1], 0, v[36:37]
	global_load_dwordx4 v[4:7], v[0:1], off nt
	s_nop 0
	global_load_dwordx4 v[0:3], v[0:1], off offset:64 nt
	s_barrier
	s_waitcnt vmcnt(6)
	ds_write_b128 v78, v[120:123]
	s_waitcnt vmcnt(5)
	ds_write_b128 v78, v[124:127] offset:18432
	s_waitcnt vmcnt(4)
	ds_write_b128 v79, v[128:131]
	s_waitcnt vmcnt(3)
	ds_write_b128 v79, v[132:135] offset:18432
	s_waitcnt vmcnt(2)
	ds_write_b128 v80, v[136:139] offset:36864
	s_waitcnt lgkmcnt(0)
	s_barrier
	ds_read_b128 v[8:11], v81
	ds_read_b128 v[12:15], v81 offset:64
	s_waitcnt vmcnt(1) lgkmcnt(1)
	v_mfma_f32_16x16x32_bf16 v[8:11], v[8:11], v[4:7], 0
	s_waitcnt vmcnt(0) lgkmcnt(0)
	v_mfma_f32_16x16x32_bf16 v[8:11], v[12:15], v[0:3], v[8:11]
	v_lshlrev_b64 v[150:151], 10, v[40:41]
	v_lshl_add_u64 v[150:151], v[150:151], 0, s[96:97]
	v_mov_b32_e32 v148, v38
	v_mov_b32_e32 v149, 0
	v_lshl_add_u64 v[150:151], v[150:151], 0, s[2:3]
	v_lshl_add_u64 v[150:151], v[150:151], 0, v[148:149]
	global_load_dwordx2 v[140:141], v[150:151], off nt
	global_load_dwordx2 v[142:143], v[150:151], off offset:32 nt
	global_load_dwordx2 v[144:145], v[150:151], off offset:64 nt
	global_load_dwordx2 v[146:147], v[150:151], off offset:96 nt
	v_mov_b32_e32 v12, 0
	v_mov_b32_e32 v13, 0
	v_mov_b32_e32 v14, 0
	v_mov_b32_e32 v15, 0
	s_and_saveexec_b64 s[0:1], s[10:11]
	s_cbranch_execz .LBB0_725
	ds_read_b128 v[12:15], v81 offset:2304
	ds_read_b128 v[16:19], v81 offset:2368
	s_waitcnt lgkmcnt(1)
	v_mfma_f32_16x16x32_bf16 v[12:15], v[12:15], v[4:7], 0
	s_waitcnt lgkmcnt(0)
	v_mfma_f32_16x16x32_bf16 v[12:15], v[16:19], v[0:3], v[12:15]
	v_mul_f32_e32 v16, v39, v47
	v_mul_f32_e32 v17, v39, v48
	v_mul_f32_e32 v18, v39, v49
	v_mul_f32_e32 v19, v39, v50
	v_exp_f32_e32 v16, v16
	v_exp_f32_e32 v17, v17
	v_exp_f32_e32 v18, v18
	v_exp_f32_e32 v19, v19
	v_pk_mul_f32 v[12:13], v[16:17], v[12:13]
	s_nop 0
	v_cndmask_b32_e64 v12, 0, v12, s[30:31]
	v_pk_mul_f32 v[14:15], v[18:19], v[14:15]
	v_cndmask_b32_e64 v13, 0, v13, s[28:29]
	v_cndmask_b32_e64 v14, 0, v14, s[26:27]
	v_cndmask_b32_e64 v15, 0, v15, s[24:25]

.LBB0_747:
	s_or_b64 exec, exec, s[0:1]
	ds_read_b128 v[84:87], v81 offset:36864
	ds_read_b128 v[88:91], v81 offset:36928
	s_lshl_b32 s0, s87, 6
	v_lshlrev_b64 v[100:101], 9, v[40:41]
	s_lshl_b32 s2, s0, 1
	s_mov_b64 s[0:1], 0x119a4400
	s_addk_i32 s33, 0x7c00
	s_waitcnt lgkmcnt(1)
	v_mfma_f32_16x16x32_bf16 v[84:87], v[84:87], v[4:7], 0
	ds_read_b128 v[92:95], v81 offset:39232
	ds_read_b128 v[96:99], v81 offset:41536
	s_waitcnt lgkmcnt(2)
	v_mfma_f32_16x16x32_bf16 v[84:87], v[88:91], v[0:3], v[84:87]
	ds_read_b128 v[88:91], v81 offset:39168
	s_waitcnt lgkmcnt(0)
	v_mfma_f32_16x16x32_bf16 v[88:91], v[88:91], v[4:7], 0
	v_mfma_f32_16x16x32_bf16 v[88:91], v[92:95], v[0:3], v[88:91]
	ds_read_b128 v[92:95], v81 offset:41472
	s_waitcnt lgkmcnt(0)
	v_mfma_f32_16x16x32_bf16 v[92:95], v[92:95], v[4:7], 0
	v_mfma_f32_16x16x32_bf16 v[92:95], v[96:99], v[0:3], v[92:95]
	ds_read_b128 v[96:99], v81 offset:43776
	s_waitcnt lgkmcnt(0)
	v_mfma_f32_16x16x32_bf16 v[4:7], v[96:99], v[4:7], 0
	ds_read_b128 v[96:99], v81 offset:43840
	s_waitcnt lgkmcnt(0)
	v_mfma_f32_16x16x32_bf16 v[2:5], v[96:99], v[0:3], v[4:7]
	v_mul_f32_e32 v0, v39, v75
	s_nop 3
	v_exp_f32_e32 v6, v0
	v_mov_b32_e32 v39, v25
	v_pk_fma_f32 v[22:23], v[6:7], v[86:87], v[22:23] op_sel_hi:[0,1,1]
	v_pk_fma_f32 v[20:21], v[6:7], v[84:85], v[20:21] op_sel_hi:[0,1,1]
	v_pk_mul_f32 v[0:1], v[22:23], v[22:23]
	v_pk_mul_f32 v[84:85], v[20:21], v[20:21]
	v_pk_fma_f32 v[14:15], v[6:7], v[90:91], v[14:15] op_sel_hi:[0,1,1]
	v_pk_mov_b32 v[86:87], v[84:85], v[0:1] op_sel:[1,0]
	v_mov_b32_e32 v85, v1
	v_pk_fma_f32 v[12:13], v[6:7], v[88:89], v[12:13] op_sel_hi:[0,1,1]
	v_pk_add_f32 v[84:85], v[86:87], v[84:85]
	v_pk_mul_f32 v[0:1], v[14:15], v[14:15]
	v_pk_mul_f32 v[86:87], v[12:13], v[12:13]
	v_pk_fma_f32 v[2:3], v[6:7], v[2:3], v[16:17] op_sel_hi:[0,1,1]
	v_pk_mov_b32 v[88:89], v[86:87], v[0:1] op_sel:[1,0]
	v_mov_b32_e32 v87, v1
	v_pk_add_f32 v[86:87], v[88:89], v[86:87]
	v_pk_fma_f32 v[10:11], v[6:7], v[94:95], v[10:11] op_sel_hi:[0,1,1]
	v_pk_fma_f32 v[8:9], v[6:7], v[92:93], v[8:9] op_sel_hi:[0,1,1]
	v_pk_fma_f32 v[0:1], v[6:7], v[4:5], v[18:19] op_sel_hi:[0,1,1]
	v_mul_f32_e32 v6, v2, v2
	v_pk_add_f32 v[4:5], v[84:85], v[84:85] op_sel:[0,1] op_sel_hi:[1,0]
	v_mul_f32_e32 v16, v3, v3
	v_mov_b32_e32 v5, v6
	v_pk_add_f32 v[6:7], v[86:87], v[86:87] op_sel:[0,1] op_sel_hi:[1,0]
	v_mul_f32_e32 v17, v0, v0
	v_mov_b32_e32 v7, v16
	v_pk_add_f32 v[4:5], v[4:5], v[6:7]
	v_mul_f32_e32 v6, v9, v9
	v_pk_fma_f32 v[6:7], v[8:9], v[8:9], v[6:7] op_sel_hi:[1,1,0]
	v_mul_f32_e32 v16, v11, v11
	v_mul_f32_e32 v18, v1, v1
	v_mov_b32_e32 v7, v17
	v_pk_fma_f32 v[16:17], v[10:11], v[10:11], v[16:17] op_sel_hi:[1,1,0]
	s_nop 0
	v_mov_b32_e32 v17, v18
	v_pk_add_f32 v[6:7], v[6:7], v[16:17]
	s_nop 0
	v_pk_add_f32 v[4:5], v[4:5], v[6:7]
	v_lshl_add_u64 v[6:7], v[100:101], 1, s[96:97]
	v_lshl_add_u64 v[6:7], v[6:7], 0, s[2:3]
	v_lshl_add_u64 v[16:17], v[6:7], 0, v[38:39]
	v_lshlrev_b64 v[6:7], 11, v[40:41]
	s_nop 0
	v_add_f32_e32 v4, v4, v5
	ds_bpermute_b32 v5, v76, v4
	v_lshl_add_u64 v[6:7], s[22:23], 0, v[6:7]
	v_lshl_add_u64 v[6:7], v[6:7], 0, s[2:3]
	v_lshl_add_u64 v[18:19], v[6:7], 0, v[38:39]
	v_lshl_add_u64 v[6:7], v[18:19], 0, s[0:1]
	s_waitcnt lgkmcnt(0)
	v_add_f32_e32 v4, v4, v5
	ds_bpermute_b32 v5, v77, v4
	s_mov_b32 s0, 0x119a4000
	v_add_co_u32_e64 v18, s[0:1], s0, v18
	s_add_i32 s2, s86, 0xf8
	s_waitcnt lgkmcnt(0)
	v_add_f32_e32 v4, v4, v5
	v_fmamk_f32 v4, v4, 0x3c800000, v82
	v_rsq_f32_e32 v4, v4
	v_addc_co_u32_e64 v19, s[0:1], 0, v19, s[0:1]
	s_mov_b64 s[0:1], 0x1f0000
	v_pk_mul_f32 v[20:21], v[20:21], v[4:5] op_sel_hi:[1,0]
	v_pk_mul_f32 v[22:23], v[22:23], v[4:5] op_sel_hi:[1,0]
	v_pk_mul_f32 v[12:13], v[12:13], v[4:5] op_sel_hi:[1,0]
	v_pk_mul_f32 v[14:15], v[14:15], v[4:5] op_sel_hi:[1,0]
	v_pk_mul_f32 v[8:9], v[8:9], v[4:5] op_sel_hi:[1,0]
	v_pk_mul_f32 v[10:11], v[10:11], v[4:5] op_sel_hi:[1,0]
	v_pk_mul_f32 v[2:3], v[2:3], v[4:5] op_sel_hi:[1,0]
	v_pk_mul_f32 v[0:1], v[0:1], v[4:5] op_sel_hi:[1,0]
	v_lshl_add_u64 v[34:35], v[34:35], 0, s[0:1]
	s_cmpk_gt_i32 s86, 0x6ef
	s_mov_b32 s86, s2
	s_waitcnt vmcnt(0)
	v_mov_b32_e32 v40, v140
	v_mov_b32_e32 v41, v141
	v_lshlrev_b32_e32 v84, 16, v40
	v_and_b32_e32 v85, 0xffff0000, v40
	v_lshlrev_b32_e32 v40, 16, v41
	v_and_b32_e32 v41, 0xffff0000, v41
	v_pk_mul_f32 v[20:21], v[20:21], v[84:85]
	v_pk_mul_f32 v[22:23], v[22:23], v[40:41]
	v_cvt_pk_bf16_f32 v20, v20, v21
	v_cvt_pk_bf16_f32 v21, v22, v23
	global_store_dwordx2 v[18:19], v[20:21], off offset:1024
	s_nop 1
	v_mov_b32_e32 v18, v142
	v_mov_b32_e32 v19, v143
	v_lshlrev_b32_e32 v20, 16, v18
	v_and_b32_e32 v21, 0xffff0000, v18
	v_lshlrev_b32_e32 v18, 16, v19
	v_and_b32_e32 v19, 0xffff0000, v19
	v_pk_mul_f32 v[12:13], v[12:13], v[20:21]
	v_pk_mul_f32 v[14:15], v[14:15], v[18:19]
	v_cvt_pk_bf16_f32 v12, v12, v13
	v_cvt_pk_bf16_f32 v13, v14, v15
	global_store_dwordx2 v[6:7], v[12:13], off offset:32
	s_nop 1
	v_mov_b32_e32 v12, v144
	v_mov_b32_e32 v13, v145
	v_lshlrev_b32_e32 v14, 16, v12
	v_and_b32_e32 v15, 0xffff0000, v12
	v_lshlrev_b32_e32 v12, 16, v13
	v_and_b32_e32 v13, 0xffff0000, v13
	v_pk_mul_f32 v[8:9], v[8:9], v[14:15]
	v_pk_mul_f32 v[10:11], v[10:11], v[12:13]
	v_cvt_pk_bf16_f32 v8, v8, v9
	v_cvt_pk_bf16_f32 v9, v10, v11
	global_store_dwordx2 v[6:7], v[8:9], off offset:64
	s_nop 1
	v_mov_b32_e32 v8, v146
	v_mov_b32_e32 v9, v147
	v_lshlrev_b32_e32 v10, 16, v8
	v_and_b32_e32 v11, 0xffff0000, v8
	v_lshlrev_b32_e32 v4, 16, v9
	v_and_b32_e32 v5, 0xffff0000, v9
	v_pk_mul_f32 v[2:3], v[2:3], v[10:11]
	v_pk_mul_f32 v[0:1], v[0:1], v[4:5]
	v_cvt_pk_bf16_f32 v2, v2, v3
	v_cvt_pk_bf16_f32 v3, v0, v1
	global_store_dwordx2 v[6:7], v[2:3], off offset:96
	s_cbranch_scc1 .LBB0_768
.LBB0_748:
	s_bfe_u32 s87, s86, 0x30005
	v_cvt_f32_ubyte0_e32 v0, s87
	v_sub_f32_e32 v0, 0xc0a00000, v0
	s_mov_b32 s0, 0xc2fc0000
	v_cmp_gt_f32_e64 s[0:1], s0, v0
	s_ashr_i32 s88, s86, 8
	s_waitcnt vmcnt(0)
	v_cndmask_b32_e64 v1, 0, v27, s[0:1]
	v_add_f32_e32 v0, v0, v1
	v_exp_f32_e32 v0, v0
	s_and_b64 s[0:1], s[0:1], exec
	s_cselect_b32 s0, 0xffffffc0, 0
	s_ashr_i32 s89, s88, 31
	v_ldexp_f32 v0, v0, s0
	s_lshl_b64 s[0:1], s[88:89], 12
	s_and_b32 s90, s33, 0xf80
	s_or_b32 s88, s0, s90
	v_sub_f32_e32 v10, 1.0, v0
	s_lshl_b32 s2, s87, 7
	v_mov_b32_e32 v1, s1
	v_or_b32_e32 v0, s88, v26
	v_lshl_add_u64 v[4:5], v[30:31], 0, s[2:3]
	v_lshlrev_b64 v[8:9], 10, v[0:1]
	v_lshl_add_u64 v[0:1], v[4:5], 0, v[8:9]
	global_load_dwordx4 v[120:123], v[0:1], off nt
	v_lshl_add_u64 v[6:7], v[32:33], 0, s[2:3]
	s_mov_b32 s89, s1
	v_add_u32_e32 v24, s90, v42
	v_lshl_add_u64 v[40:41], s[0:1], 0, v[24:25]
	v_log_f32_e32 v39, v10
	v_lshl_add_u64 v[0:1], v[6:7], 0, v[8:9]
	global_load_dwordx4 v[124:127], v[0:1], off nt
	v_lshl_add_u64 v[0:1], s[88:89], 0, v[28:29]
	v_lshlrev_b64 v[8:9], 10, v[0:1]
	v_lshl_add_u64 v[0:1], v[4:5], 0, v[8:9]
	global_load_dwordx4 v[128:131], v[0:1], off nt
	v_lshl_add_u64 v[0:1], v[6:7], 0, v[8:9]
	global_load_dwordx4 v[132:135], v[0:1], off nt
	global_load_dwordx4 v[136:139], v[34:35], off nt
	v_lshlrev_b64 v[0:1], 10, v[40:41]
	v_lshl_add_u64 v[0:1], s[94:95], 0, v[0:1]
	v_lshl_add_u64 v[0:1], v[0:1], 0, s[2:3]
	v_lshl_add_u64 v[0:1], v[0:1], 0, v[36:37]
	global_load_dwordx4 v[4:7], v[0:1], off nt
	s_nop 0
	global_load_dwordx4 v[0:3], v[0:1], off offset:64 nt
	s_barrier
	s_waitcnt vmcnt(6)
	ds_write_b128 v78, v[120:123]
	s_waitcnt vmcnt(5)
	ds_write_b128 v78, v[124:127] offset:18432
	s_waitcnt vmcnt(4)
	ds_write_b128 v79, v[128:131]
	s_waitcnt vmcnt(3)
	ds_write_b128 v79, v[132:135] offset:18432
	s_waitcnt vmcnt(2)
	ds_write_b128 v80, v[136:139] offset:36864
	s_waitcnt lgkmcnt(0)
	s_barrier
	ds_read_b128 v[8:11], v81
	ds_read_b128 v[12:15], v81 offset:64
	s_waitcnt vmcnt(1) lgkmcnt(1)
	v_mfma_f32_16x16x32_bf16 v[8:11], v[8:11], v[4:7], 0
	s_waitcnt vmcnt(0) lgkmcnt(0)
	v_mfma_f32_16x16x32_bf16 v[8:11], v[12:15], v[0:3], v[8:11]
	v_lshlrev_b64 v[150:151], 10, v[40:41]
	v_lshl_add_u64 v[150:151], v[150:151], 0, s[96:97]
	v_mov_b32_e32 v148, v38
	v_mov_b32_e32 v149, 0
	v_lshl_add_u64 v[150:151], v[150:151], 0, s[2:3]
	v_lshl_add_u64 v[150:151], v[150:151], 0, v[148:149]
	global_load_dwordx2 v[140:141], v[150:151], off nt
	global_load_dwordx2 v[142:143], v[150:151], off offset:32 nt
	global_load_dwordx2 v[144:145], v[150:151], off offset:64 nt
	global_load_dwordx2 v[146:147], v[150:151], off offset:96 nt
	v_mov_b32_e32 v12, 0
	v_mov_b32_e32 v13, 0
	v_mov_b32_e32 v14, 0
	v_mov_b32_e32 v15, 0
	s_and_saveexec_b64 s[0:1], s[10:11]
	s_cbranch_execz .LBB0_750
	ds_read_b128 v[12:15], v81 offset:2304
	ds_read_b128 v[16:19], v81 offset:2368
	s_waitcnt lgkmcnt(1)
	v_mfma_f32_16x16x32_bf16 v[12:15], v[12:15], v[4:7], 0
	s_waitcnt lgkmcnt(0)
	v_mfma_f32_16x16x32_bf16 v[12:15], v[16:19], v[0:3], v[12:15]
	v_mul_f32_e32 v16, v39, v47
	v_mul_f32_e32 v17, v39, v48
	v_mul_f32_e32 v18, v39, v49
	v_mul_f32_e32 v19, v39, v50
	v_exp_f32_e32 v16, v16
	v_exp_f32_e32 v17, v17
	v_exp_f32_e32 v18, v18
	v_exp_f32_e32 v19, v19
	v_pk_mul_f32 v[12:13], v[16:17], v[12:13]
	s_nop 0
	v_cndmask_b32_e64 v12, 0, v12, s[30:31]
	v_pk_mul_f32 v[14:15], v[18:19], v[14:15]
	v_cndmask_b32_e64 v13, 0, v13, s[28:29]
	v_cndmask_b32_e64 v14, 0, v14, s[26:27]
	v_cndmask_b32_e64 v15, 0, v15, s[24:25]
